# speedup vs baseline: 1.0071x; 1.0071x over previous
; __device__ __forceinline__ float bflo(unsigned w) { return __uint_as_float(w << 16); }
; __device__ __forceinline__ float bfhi(unsigned w) { return __uint_as_float(w & 0xffff0000u); }
; __global__ void __launch_bounds__(NTHR, 2) fwd_megakernel(Args a_unused) {
;     ...
;         for (int row = bid * NWAVES + wave; row < M; row += G * NWAVES) {
;             const f32x4 p0 = *(const f32x4*)(part0 + (size_t)row * 16), p1 = *(const f32x4*)(part0 + (size_t)row * 16 + 4), p2 = *(const f32x4*)(part0 + (size_t)row * 16 + 8), p3 = *(const f32x4*)(part0 + (size_t)row * 16 + 12);
;             const float ss = ((p0.x + p0.y) + (p0.z + p0.w)) + ((p1.x + p1.y) + (p1.z + p1.w)) + ((p2.x + p2.y) + (p2.z + p2.w)) + ((p3.x + p3.y) + (p3.z + p3.w));
;             const float rstd = rsqrtf(ss * (1.0f / D) + EPS);
; #pragma unroll
;             for (int j = 0; j < 4; ++j) { const size_t o = (size_t)row * D + 4 * lane + 256 * j; const u32x2 w = __builtin_nontemporal_load((const u32x2*)(hbp + o));
;                 f32x4 v = {bflo(w.x), bfhi(w.x), bflo(w.y), bfhi(w.y)}; v = v * rstd * gv[j]; __builtin_nontemporal_store(v, (f32x4*)(out + o)); }
;         }
.LBB0_941:
	global_load_dwordx4 v[22:25], v17, s[0:1] offset:-48
	global_load_dwordx4 v[26:29], v17, s[0:1] offset:-32
	global_load_dwordx4 v[30:33], v17, s[0:1] offset:-16
	global_load_dwordx4 v[34:37], v17, s[0:1]
	global_load_dwordx2 v[38:39], v[18:19], off offset:-1024 nt
	global_load_dwordx2 v[40:41], v[18:19], off offset:-512 nt
	global_load_dwordx2 v[42:43], v[18:19], off nt
	global_load_dwordx2 v[44:45], v[18:19], off offset:512 nt
	s_add_i32 s8, s8, s10
	s_add_u32 s0, s0, s2
	s_addc_u32 s1, s1, s3
	v_lshl_add_u64 v[18:19], v[18:19], 0, s[4:5]
	s_waitcnt vmcnt(0)
	v_add_f32_e32 v22, v22, v23
	v_add_f32_e32 v24, v24, v25
	v_add_f32_e32 v22, v22, v24
	v_add_f32_e32 v26, v26, v27
	v_add_f32_e32 v28, v28, v29
	v_add_f32_e32 v26, v26, v28
	v_add_f32_e32 v30, v30, v31
	v_add_f32_e32 v32, v32, v33
	v_add_f32_e32 v30, v30, v32
	v_add_f32_e32 v34, v34, v35
	v_add_f32_e32 v36, v36, v37
	v_add_f32_e32 v34, v34, v36
	v_add_f32_e32 v22, v22, v26
	v_add_f32_e32 v22, v22, v30
	v_add_f32_e32 v22, v22, v34
	v_fmamk_f32 v22, v22, 0x3a800000, v16
	v_mul_f32_e32 v23, 0x4b800000, v22
	v_cmp_gt_f32_e32 vcc, s9, v22
	s_nop 1
	v_cndmask_b32_e32 v22, v22, v23, vcc
	v_rsq_f32_e32 v22, v22
	s_nop 0
	v_mul_f32_e32 v23, 0x45800000, v22
	v_cndmask_b32_e32 v26, v22, v23, vcc
	v_lshlrev_b32_e32 v46, 16, v38
	v_and_b32_e32 v47, 0xffff0000, v38
	v_lshlrev_b32_e32 v48, 16, v39
	v_and_b32_e32 v49, 0xffff0000, v39
	v_pk_mul_f32 v[46:47], v[26:27], v[46:47] op_sel_hi:[0,1]
	v_pk_mul_f32 v[48:49], v[26:27], v[48:49] op_sel_hi:[0,1]
	v_pk_mul_f32 v[46:47], v[0:1], v[46:47]
	v_pk_mul_f32 v[48:49], v[2:3], v[48:49]
	global_store_dwordx4 v[20:21], v[46:49], off offset:-2048 nt
	v_lshlrev_b32_e32 v50, 16, v40
	v_and_b32_e32 v51, 0xffff0000, v40
	v_lshlrev_b32_e32 v52, 16, v41
	v_and_b32_e32 v53, 0xffff0000, v41
	v_pk_mul_f32 v[50:51], v[26:27], v[50:51] op_sel_hi:[0,1]
	v_pk_mul_f32 v[52:53], v[26:27], v[52:53] op_sel_hi:[0,1]
	v_pk_mul_f32 v[50:51], v[4:5], v[50:51]
	v_pk_mul_f32 v[52:53], v[6:7], v[52:53]
	global_store_dwordx4 v[20:21], v[50:53], off offset:-1024 nt
	v_lshlrev_b32_e32 v54, 16, v42
	v_and_b32_e32 v55, 0xffff0000, v42
	v_lshlrev_b32_e32 v56, 16, v43
	v_and_b32_e32 v57, 0xffff0000, v43
	v_pk_mul_f32 v[54:55], v[26:27], v[54:55] op_sel_hi:[0,1]
	v_pk_mul_f32 v[56:57], v[26:27], v[56:57] op_sel_hi:[0,1]
	v_pk_mul_f32 v[54:55], v[8:9], v[54:55]
	v_pk_mul_f32 v[56:57], v[10:11], v[56:57]
	global_store_dwordx4 v[20:21], v[54:57], off nt
	v_lshlrev_b32_e32 v58, 16, v44
	v_and_b32_e32 v59, 0xffff0000, v44
	v_lshlrev_b32_e32 v60, 16, v45
	v_and_b32_e32 v61, 0xffff0000, v45
	v_pk_mul_f32 v[58:59], v[26:27], v[58:59] op_sel_hi:[0,1]
	v_pk_mul_f32 v[60:61], v[26:27], v[60:61] op_sel_hi:[0,1]
	v_pk_mul_f32 v[58:59], v[12:13], v[58:59]
	v_pk_mul_f32 v[60:61], v[14:15], v[60:61]
	global_store_dwordx4 v[20:21], v[58:61], off offset:1024 nt
	v_lshl_add_u64 v[20:21], v[20:21], 0, s[6:7]
	s_cmpk_gt_i32 s8, 0x3fff
	s_cbranch_scc0 .LBB0_941
